# up-proj: L2 warm-up loads for the next tile's first two K-tiles issued mid-epilogue
# speedup vs baseline: 1.0023x; 1.0023x over previous
.LBB0_94:
	s_or_b64 exec, exec, s[0:1]
	s_waitcnt vmcnt(0)
	v_readlane_b32 s16, v255, 44
	s_add_i32 s16, s11, s16
	s_cmpk_gt_i32 s16, 0x83f
	s_cbranch_scc1 .Lpf8_skip
	s_mul_hi_u32 s17, s16, 0x2e8ba2e9
	s_lshr_b32 s17, s17, 5
	s_mul_i32 s28, s17, 0xb0
	s_sub_i32 s28, s16, s28
	s_lshl_b32 s28, s28, 4
	s_and_b32 s28, s28, 0xffffff80
	s_and_b32 s70, s16, 7
	s_lshl_b32 s17, s17, 3
	s_or_b32 s17, s17, s70
	s_lshl_b32 s17, s17, 8
	s_lshr_b32 s59, s17, 21
	s_lshl_b32 s58, s17, 11
	v_readlane_b32 s86, v255, 26
	v_readlane_b32 s87, v255, 27
	s_add_u32 s58, s86, s58
	s_addc_u32 s59, s87, s59
	s_lshr_b32 s83, s28, 21
	s_lshl_b32 s82, s28, 11
	s_add_u32 s82, s6, s82
	s_addc_u32 s83, s7, s83
	v_lshrrev_b32_e32 v250, 1, v166
	v_and_b32_e32 v251, 1, v166
	v_lshlrev_b32_e32 v251, 7, v251
	v_lshl_or_b32 v250, v250, 11, v251
	v_lshrrev_b32_e32 v251, 8, v166
	v_mul_u32_u24_e32 v251, 0x540000, v251
	v_add_u32_e32 v251, v251, v250
	global_load_dword v250, v250, s[58:59]
	global_load_dword v251, v251, s[82:83]
.Lpf8_skip:
	v_pk_fma_f32 v[112:113], v[50:51], v[112:113], v[62:63]
	v_pk_fma_f32 v[110:111], v[52:53], v[110:111], v[64:65]
	v_pk_fma_f32 v[112:113], v[54:55], v[88:89], v[112:113]
	v_pk_fma_f32 v[110:111], v[56:57], v[86:87], v[110:111]
	v_pk_fma_f32 v[112:113], v[58:59], v[126:127], v[112:113]
	v_pk_fma_f32 v[110:111], v[60:61], v[120:121], v[110:111]
	v_mul_f32_e32 v73, 0xbfb8aa3b, v112
	v_mul_f32_e32 v116, 0xbfb8aa3b, v113
	v_exp_f32_e32 v73, v73
	v_exp_f32_e32 v116, v116
	v_pk_fma_f32 v[106:107], v[34:35], v[106:107], v[46:47]
	v_pk_fma_f32 v[104:105], v[18:19], v[104:105], v[30:31]
	v_add_f32_e32 v73, 1.0, v73
	v_add_f32_e32 v117, 1.0, v116
	v_rcp_f32_e32 v116, v73
	v_rcp_f32_e32 v117, v117
	v_mul_f32_e32 v73, 0xbfb8aa3b, v110
	v_exp_f32_e32 v73, v73
	v_pk_fma_f32 v[106:107], v[38:39], v[84:85], v[106:107]
	v_pk_mul_f32 v[112:113], v[112:113], v[116:117]
	v_mul_f32_e32 v116, 0xbfb8aa3b, v111
	v_exp_f32_e32 v116, v116
	v_pk_fma_f32 v[106:107], v[42:43], v[114:115], v[106:107]
	v_add_f32_e32 v73, 1.0, v73
	v_pk_mul_f32 v[106:107], v[106:107], v[112:113]
	v_rcp_f32_e32 v112, v73
	v_add_f32_e32 v73, 1.0, v116
	v_rcp_f32_e32 v113, v73
	v_pk_fma_f32 v[104:105], v[22:23], v[82:83], v[104:105]
	v_pk_fma_f32 v[100:101], v[36:37], v[100:101], v[48:49]
	v_pk_fma_f32 v[104:105], v[26:27], v[108:109], v[104:105]
	v_pk_mul_f32 v[110:111], v[110:111], v[112:113]
	v_mul_f32_e32 v73, 0xbfb8aa3b, v104
	v_exp_f32_e32 v73, v73
	v_mul_f32_e32 v112, 0xbfb8aa3b, v105
	v_exp_f32_e32 v112, v112
	v_pk_fma_f32 v[100:101], v[40:41], v[80:81], v[100:101]
	v_add_f32_e32 v73, 1.0, v73
	v_pk_fma_f32 v[100:101], v[44:45], v[102:103], v[100:101]
	v_pk_fma_f32 v[98:99], v[20:21], v[98:99], v[32:33]
	v_pk_mul_f32 v[100:101], v[100:101], v[110:111]
	v_rcp_f32_e32 v110, v73
	v_add_f32_e32 v73, 1.0, v112
	v_rcp_f32_e32 v111, v73
	v_pk_fma_f32 v[98:99], v[24:25], v[76:77], v[98:99]
	v_pk_fma_f32 v[94:95], v[2:3], v[94:95], v[14:15]
	v_pk_fma_f32 v[98:99], v[28:29], v[96:97], v[98:99]
	v_pk_mul_f32 v[104:105], v[104:105], v[110:111]
	v_mul_f32_e32 v73, 0xbfb8aa3b, v98
	v_exp_f32_e32 v73, v73
	v_mul_f32_e32 v110, 0xbfb8aa3b, v99
	v_exp_f32_e32 v110, v110
	v_pk_fma_f32 v[94:95], v[6:7], v[74:75], v[94:95]
	v_add_f32_e32 v73, 1.0, v73
	v_pk_fma_f32 v[94:95], v[10:11], v[92:93], v[94:95]
	v_pk_fma_f32 v[78:79], v[4:5], v[78:79], v[16:17]
	v_pk_mul_f32 v[94:95], v[94:95], v[104:105]
	v_rcp_f32_e32 v104, v73
	v_add_f32_e32 v73, 1.0, v110
	v_rcp_f32_e32 v105, v73
	v_pk_fma_f32 v[78:79], v[8:9], v[70:71], v[78:79]
	v_mov_b32_e32 v73, 0
	v_pk_fma_f32 v[78:79], v[12:13], v[90:91], v[78:79]
	v_pk_mul_f32 v[98:99], v[98:99], v[104:105]
	v_mov_b32_e32 v118, 0
	v_pk_mul_f32 v[78:79], v[78:79], v[98:99]
	v_cvt_pk_bf16_f32 v99, v100, v101
	v_cvt_pk_bf16_f32 v101, v78, v79
	v_add_co_u32_e32 v78, vcc, 0x1000, v68
	v_cvt_pk_bf16_f32 v98, v106, v107
	v_cvt_pk_bf16_f32 v100, v94, v95
	v_addc_co_u32_e32 v79, vcc, 0, v69, vcc
	global_store_dwordx4 v[78:79], v[98:101], off offset:1536
	v_mov_b32_e32 v94, 0
	v_mov_b32_e32 v95, 0
	v_mov_b32_e32 v78, 0
	v_mov_b32_e32 v79, 0
	v_mov_b32_e32 v106, 0
	v_mov_b32_e32 v107, 0
	v_mov_b32_e32 v100, 0
	v_mov_b32_e32 v101, 0
	v_mov_b32_e32 v119, 0
	v_mov_b32_e32 v112, 0
	v_mov_b32_e32 v113, 0
	v_mov_b32_e32 v124, 0
	v_mov_b32_e32 v125, 0
	s_and_saveexec_b64 s[0:1], s[42:43]
	s_cbranch_execz .LBB0_96
	ds_read_b128 v[104:107], v130 offset:1584
	ds_read_b128 v[132:135], v130 offset:1840
	s_waitcnt lgkmcnt(1)
	v_lshlrev_b32_e32 v112, 16, v104
	v_and_b32_e32 v113, 0xffff0000, v104
	v_lshlrev_b32_e32 v100, 16, v105
	v_and_b32_e32 v101, 0xffff0000, v105
	v_lshlrev_b32_e32 v78, 16, v106
	v_and_b32_e32 v79, 0xffff0000, v106
	v_lshlrev_b32_e32 v72, 16, v107
	v_and_b32_e32 v73, 0xffff0000, v107
	s_waitcnt lgkmcnt(0)
	v_lshlrev_b32_e32 v124, 16, v132
	v_and_b32_e32 v125, 0xffff0000, v132
	v_lshlrev_b32_e32 v118, 16, v133
	v_and_b32_e32 v119, 0xffff0000, v133
	v_lshlrev_b32_e32 v106, 16, v134
	v_and_b32_e32 v107, 0xffff0000, v134
	v_lshlrev_b32_e32 v94, 16, v135
	v_and_b32_e32 v95, 0xffff0000, v135
